# GDN scan compute waves: LDS fragment reads double-buffered one MFMA ahead (17 of 30 chain links), on top of the r38 stack
# baseline (speedup 1.0000x reference)
.LBB0_939:
	s_andn2_saveexec_b64 s[2:3], s[26:27]
	s_cbranch_execz .LBB0_906
	s_and_b32 s25, s31, 1
	s_mul_i32 s26, s25, 0xaa00
	s_add_i32 s26, s26, 0
	v_add3_u32 v1, s26, v213, v214
	v_add_u32_e32 v1, 0x8800, v1
	ds_read2_b64 v[6:9], v1 offset1:2
	v_add3_u32 v15, s26, v215, v214
	ds_read2_b64 v[10:13], v1 offset0:4 offset1:6
	v_cvt_pk_bf16_f32 v2, v16, v17
	v_cvt_pk_bf16_f32 v3, v18, v19
	s_waitcnt lgkmcnt(1)
	v_lshlrev_b32_e32 v80, 16, v6
	v_and_b32_e32 v81, 0xffff0000, v6
	v_lshlrev_b32_e32 v82, 16, v7
	v_and_b32_e32 v83, 0xffff0000, v7
	v_lshlrev_b32_e32 v84, 16, v8
	v_and_b32_e32 v85, 0xffff0000, v8
	v_lshlrev_b32_e32 v86, 16, v9
	v_and_b32_e32 v87, 0xffff0000, v9
	ds_read2_b64 v[6:9], v15 offset1:2
	v_cvt_pk_bf16_f32 v4, v20, v21
	v_cvt_pk_bf16_f32 v5, v22, v23
	s_waitcnt lgkmcnt(1)
	v_lshlrev_b32_e32 v88, 16, v10
	v_and_b32_e32 v89, 0xffff0000, v10
	v_lshlrev_b32_e32 v90, 16, v11
	v_and_b32_e32 v91, 0xffff0000, v11
	v_lshlrev_b32_e32 v92, 16, v12
	v_and_b32_e32 v93, 0xffff0000, v12
	v_lshlrev_b32_e32 v94, 16, v13
	v_and_b32_e32 v95, 0xffff0000, v13
	v_add_u32_e32 v14, 0x2000, v15
	v_cvt_pk_bf16_f32 v10, v24, v25
	ds_read2_b64 v[228:231], v14 offset0:64 offset1:66
	s_waitcnt lgkmcnt(1)
	v_mfma_f32_32x32x16_bf16 v[80:95], v[6:9], v[2:5], v[80:95]
	v_cvt_pk_bf16_f32 v11, v26, v27
	v_cvt_pk_bf16_f32 v12, v28, v29
	v_cvt_pk_bf16_f32 v13, v30, v31
	v_cvt_pk_bf16_f32 v220, v32, v33
	v_cvt_pk_bf16_f32 v221, v34, v35
	v_cvt_pk_bf16_f32 v222, v36, v37
	ds_read2_b64 v[6:9], v15 offset0:4 offset1:6
	s_waitcnt lgkmcnt(1)
	v_mfma_f32_32x32x16_bf16 v[48:63], v[228:231], v[2:5], 0
	v_cvt_pk_bf16_f32 v223, v38, v39
	v_cvt_pk_bf16_f32 v224, v40, v41
	v_cvt_pk_bf16_f32 v225, v42, v43
	v_cvt_pk_bf16_f32 v226, v44, v45
	v_cvt_pk_bf16_f32 v227, v46, v47
	s_lshl_b32 s26, s31, 2
	ds_read2_b64 v[228:231], v14 offset0:68 offset1:70
	s_waitcnt lgkmcnt(1)
	v_mfma_f32_32x32x16_bf16 v[80:95], v[6:9], v[10:13], v[80:95]
	s_add_i32 s26, s26, 0
	s_add_i32 s26, s26, 0x23c00
	s_mulk_i32 s25, 0x4100
	ds_read2_b64 v[6:9], v15 offset0:8 offset1:10
	s_waitcnt lgkmcnt(1)
	v_mfma_f32_32x32x16_bf16 v[48:63], v[228:231], v[10:13], v[48:63]
	ds_read2_b64 v[228:231], v14 offset0:72 offset1:74
	s_waitcnt lgkmcnt(1)
	v_mfma_f32_32x32x16_bf16 v[80:95], v[6:9], v[220:223], v[80:95]
	ds_read2_b64 v[6:9], v15 offset0:12 offset1:14
	s_waitcnt lgkmcnt(1)
	v_mfma_f32_32x32x16_bf16 v[48:63], v[228:231], v[220:223], v[48:63]
	ds_read2_b64 v[228:231], v14 offset0:76 offset1:78
	s_waitcnt lgkmcnt(1)
	v_mfma_f32_32x32x16_bf16 v[80:95], v[6:9], v[224:227], v[80:95]
	ds_read2_b64 v[64:67], v1 offset0:8 offset1:10
	v_add_u32_e32 v14, 0x3000, v15
	s_waitcnt lgkmcnt(0)
	v_lshlrev_b32_e32 v96, 16, v64
	v_and_b32_e32 v97, 0xffff0000, v64
	v_mfma_f32_32x32x16_bf16 v[48:63], v[228:231], v[224:227], v[48:63]
	ds_read2_b64 v[6:9], v1 offset0:12 offset1:14
	v_add_u32_e32 v1, 0x1000, v15
	v_lshlrev_b32_e32 v98, 16, v65
	v_and_b32_e32 v99, 0xffff0000, v65
	v_lshlrev_b32_e32 v100, 16, v66
	v_and_b32_e32 v101, 0xffff0000, v66
	v_lshlrev_b32_e32 v102, 16, v67
	v_and_b32_e32 v103, 0xffff0000, v67
	ds_read2_b64 v[64:67], v1 offset0:32 offset1:34
	s_waitcnt lgkmcnt(1)
	v_lshlrev_b32_e32 v104, 16, v6
	v_and_b32_e32 v105, 0xffff0000, v6
	v_lshlrev_b32_e32 v106, 16, v7
	v_and_b32_e32 v107, 0xffff0000, v7
	v_lshlrev_b32_e32 v108, 16, v8
	v_and_b32_e32 v109, 0xffff0000, v8
	v_lshlrev_b32_e32 v110, 16, v9
	v_and_b32_e32 v111, 0xffff0000, v9
	ds_read2_b64 v[6:9], v14 offset0:96 offset1:98
	s_waitcnt lgkmcnt(1)
	v_mfma_f32_32x32x16_bf16 v[96:111], v[64:67], v[2:5], v[96:111]
	s_waitcnt lgkmcnt(0)
	v_mfma_f32_32x32x16_bf16 v[64:79], v[6:9], v[2:5], 0
	ds_read2_b64 v[2:5], v1 offset0:36 offset1:38
	v_cvt_pk_bf16_f32 v6, v80, v81
	v_cvt_pk_bf16_f32 v7, v82, v83
	v_cvt_pk_bf16_f32 v8, v84, v85
	v_cvt_pk_bf16_f32 v9, v86, v87
	ds_read2_b64 v[228:231], v14 offset0:100 offset1:102
	s_waitcnt lgkmcnt(1)
	v_mfma_f32_32x32x16_bf16 v[96:111], v[2:5], v[10:13], v[96:111]
	ds_read2_b64 v[2:5], v1 offset0:40 offset1:42
	s_waitcnt lgkmcnt(1)
	v_mfma_f32_32x32x16_bf16 v[64:79], v[228:231], v[10:13], v[64:79]
	v_cvt_pk_bf16_f32 v10, v88, v89
	v_cvt_pk_bf16_f32 v11, v90, v91
	v_cvt_pk_bf16_f32 v12, v92, v93
	v_cvt_pk_bf16_f32 v13, v94, v95
	ds_read2_b64 v[228:231], v14 offset0:104 offset1:106
	s_waitcnt lgkmcnt(1)
	v_mfma_f32_32x32x16_bf16 v[96:111], v[2:5], v[220:223], v[96:111]
	ds_read2_b64 v[2:5], v1 offset0:44 offset1:46
	s_waitcnt lgkmcnt(1)
	v_mfma_f32_32x32x16_bf16 v[64:79], v[228:231], v[220:223], v[64:79]
	v_add_u32_e32 v1, 0x4000, v15
	ds_read2_b64 v[228:231], v14 offset0:108 offset1:110
	s_waitcnt lgkmcnt(1)
	v_mfma_f32_32x32x16_bf16 v[96:111], v[2:5], v[224:227], v[96:111]
	ds_read2_b64 v[2:5], v1 offset0:128 offset1:130
	s_waitcnt lgkmcnt(1)
	v_mfma_f32_32x32x16_bf16 v[64:79], v[228:231], v[224:227], v[64:79]
	ds_read2_b64 v[228:231], v1 offset0:132 offset1:134
	s_waitcnt lgkmcnt(1)
	v_mfma_f32_32x32x16_bf16 v[48:63], v[2:5], v[6:9], v[48:63]
	v_add_u32_e32 v1, 0x5000, v15
	ds_read2_b64 v[2:5], v1 offset0:160 offset1:162
	s_waitcnt lgkmcnt(1)
	v_mfma_f32_32x32x16_bf16 v[48:63], v[228:231], v[10:13], v[48:63]
	ds_read2_b64 v[228:231], v1 offset0:164 offset1:166
	s_waitcnt lgkmcnt(1)
	v_mfma_f32_32x32x16_bf16 v[64:79], v[2:5], v[6:9], v[64:79]
	ds_read2_b64 v[80:83], v1 offset0:168 offset1:170
	ds_read2_b64 v[84:87], v1 offset0:172 offset1:174
	v_mov_b32_e32 v1, s26
	ds_read_b32 v14, v1
	v_add_u32_e32 v1, 0x6000, v15
	s_waitcnt lgkmcnt(0)
	v_pk_mul_f32 v[30:31], v[30:31], v[14:15] op_sel_hi:[1,0]
	v_mfma_f32_32x32x16_bf16 v[64:79], v[228:231], v[10:13], v[64:79]
	v_cvt_pk_bf16_f32 v2, v96, v97
	v_cvt_pk_bf16_f32 v3, v98, v99
	v_cvt_pk_bf16_f32 v4, v100, v101
	v_cvt_pk_bf16_f32 v5, v102, v103
	v_mul_f32_e64 v28, v28, v14
	v_mul_f32_e64 v29, v29, v14
	v_pk_mul_f32 v[26:27], v[26:27], v[14:15] op_sel_hi:[1,0]
	v_pk_mul_f32 v[24:25], v[24:25], v[14:15] op_sel_hi:[1,0]
	v_mfma_f32_32x32x16_bf16 v[64:79], v[80:83], v[2:5], v[64:79]
	v_cvt_pk_bf16_f32 v80, v104, v105
	v_cvt_pk_bf16_f32 v81, v106, v107
	v_cvt_pk_bf16_f32 v82, v108, v109
	v_cvt_pk_bf16_f32 v83, v110, v111
	v_mul_f32_e64 v22, v22, v14
	v_mul_f32_e64 v23, v23, v14
	v_pk_mul_f32 v[20:21], v[20:21], v[14:15] op_sel_hi:[1,0]
	v_pk_mul_f32 v[18:19], v[18:19], v[14:15] op_sel_hi:[1,0]
	v_mfma_f32_32x32x16_bf16 v[64:79], v[84:87], v[80:83], v[64:79]
	ds_read2_b64 v[84:87], v1 offset0:192 offset1:194
	v_mul_f32_e64 v16, v16, v14
	v_mul_f32_e64 v17, v17, v14
	v_mul_f32_e64 v46, v46, v14
	v_mul_f32_e64 v47, v47, v14
	v_pk_mul_f32 v[44:45], v[44:45], v[14:15] op_sel_hi:[1,0]
	v_pk_mul_f32 v[42:43], v[42:43], v[14:15] op_sel_hi:[1,0]
	v_pk_mul_f32 v[40:41], v[40:41], v[14:15] op_sel_hi:[1,0]
	v_pk_mul_f32 v[38:39], v[38:39], v[14:15] op_sel_hi:[1,0]
	ds_read2_b64 v[228:231], v1 offset0:196 offset1:198
	s_waitcnt lgkmcnt(1)
	v_mfma_f32_32x32x16_bf16 v[16:31], v[84:87], v[6:9], v[16:31]
	v_mul_f32_e64 v36, v36, v14
	v_mul_f32_e64 v37, v37, v14
	v_mul_f32_e64 v34, v34, v14
	v_mul_f32_e64 v35, v35, v14
	v_pk_mul_f32 v[32:33], v[32:33], v[14:15] op_sel_hi:[1,0]
	s_waitcnt lgkmcnt(0)
	v_mfma_f32_32x32x16_bf16 v[16:31], v[228:231], v[10:13], v[16:31]
	ds_read2_b64 v[84:87], v1 offset0:200 offset1:202
	ds_read2_b64 v[88:91], v1 offset0:204 offset1:206
	v_add_u32_e32 v1, 0x7000, v15
	s_waitcnt lgkmcnt(1)
	v_mfma_f32_32x32x16_bf16 v[16:31], v[84:87], v[2:5], v[16:31]
	ds_read2_b64 v[84:87], v1 offset0:224 offset1:226
	s_waitcnt lgkmcnt(0)
	v_mfma_f32_32x32x16_bf16 v[32:47], v[84:87], v[6:9], v[32:47]
	v_mfma_f32_32x32x16_bf16 v[16:31], v[88:91], v[80:83], v[16:31]
	ds_read2_b64 v[88:91], v1 offset0:228 offset1:230
	ds_read2_b64 v[92:95], v1 offset0:232 offset1:234
	ds_read2_b64 v[96:99], v1 offset0:236 offset1:238
	v_add_u32_e32 v1, s25, v216
	v_add_u32_e32 v6, 0x800, v1
	ds_write2_b32 v1, v48, v49 offset1:65
	ds_write2_b32 v1, v50, v51 offset0:130 offset1:195
	ds_write2_b32 v6, v52, v53 offset0:8 offset1:73
	ds_write2_b32 v6, v54, v55 offset0:138 offset1:203
	v_add_u32_e32 v6, 0x1000, v1
	s_waitcnt lgkmcnt(6)
	v_mfma_f32_32x32x16_bf16 v[32:47], v[88:91], v[10:13], v[32:47]
	ds_write2_b32 v6, v56, v57 offset0:16 offset1:81
	ds_write2_b32 v6, v58, v59 offset0:146 offset1:211
	v_add_u32_e32 v6, 0x1800, v1
	ds_write2_b32 v6, v60, v61 offset0:24 offset1:89
	ds_write2_b32 v6, v62, v63 offset0:154 offset1:219
	v_add_u32_e32 v6, 0x2000, v1
	ds_write2_b32 v6, v64, v65 offset0:32 offset1:97
	ds_write2_b32 v6, v66, v67 offset0:162 offset1:227
	v_add_u32_e32 v6, 0x2800, v1
	ds_write2_b32 v6, v68, v69 offset0:40 offset1:105
	ds_write2_b32 v6, v70, v71 offset0:170 offset1:235
	s_waitcnt lgkmcnt(13)
	v_mfma_f32_32x32x16_bf16 v[32:47], v[92:95], v[2:5], v[32:47]
	v_add_u32_e32 v2, 0x3000, v1
	v_add_u32_e32 v1, 0x3800, v1
	ds_write2_b32 v2, v72, v73 offset0:48 offset1:113
	ds_write2_b32 v2, v74, v75 offset0:178 offset1:243
	ds_write2_b32 v1, v76, v77 offset0:56 offset1:121
	ds_write2_b32 v1, v78, v79 offset0:186 offset1:251
	s_waitcnt lgkmcnt(14)
	v_mfma_f32_32x32x16_bf16 v[32:47], v[96:99], v[80:83], v[32:47]
	s_branch .LBB0_906
